# v11 plus SSD state-update MFMAs issued as adjacent accumulate pairs (no dependent MFMA at a 2..4 slot distance)
# baseline (speedup 1.0000x reference)
; #define LAS __attribute__((address_space(3)))
; __device__ __forceinline__ unsigned pkbf(float lo, float hi) { f32x2v v = {lo, hi}; bf16x2v b = __builtin_convertvector(v, bf16x2v); return __builtin_bit_cast(unsigned, b); }
; DI float bf_lo(unsigned w) { return __uint_as_float(w << 16); }
; DI float bf_hi(unsigned w) { return __uint_as_float(w & 0xffff0000u); }
; DI float silu_f(float x) { return x * __builtin_amdgcn_rcpf(1.0f + __builtin_amdgcn_exp2f(-1.4426950408889634f * x)); }
; #define MFMA16(a, b, c) __builtin_amdgcn_mfma_f32_16x16x32_bf16((a), (b), (c), 0, 0, 0)
; DI void ssd_unit(LAS unsigned char* lds, const bf16* XBC, const float* DT, const bf16* PROJ, bf16* YG, int rb, int NC, int h, float A, float Dsk, const float* h0, float* hout, int tid) {
;     ...
;             const float x0 = bf_lo(gx[pt].x), x1 = bf_hi(gx[pt].x), x2 = bf_lo(gx[pt].y), x3 = bf_hi(gx[pt].y);
;             const float z0 = bf_lo(gz[pt].x), z1 = bf_hi(gz[pt].x), z2 = bf_lo(gz[pt].y), z3 = bf_hi(gz[pt].y);
;             u32x2 w; w.x = pkbf((y[0] + Dsk * x0) * silu_f(z0), (y[1] + Dsk * x1) * silu_f(z1)); w.y = pkbf((y[2] + Dsk * x2) * silu_f(z2), (y[3] + Dsk * x3) * silu_f(z3));
;             *(u32x2*)(YG + (size_t)(row0 + i) * 2048 + h * 64 + 16 * pb + 4 * quad) = w;
;         }
;         const float et = __expf(atot);
; #pragma unroll
;         for (int t = 0; t < 4; ++t) hacc[t] *= et;
; #pragma unroll
;         for (int s = 0; s < 2; ++s) {
;             const bf16x8 xf = tr_frag(T + XW, RSX, 32 * s, 16 * pbk, lane);
; #pragma unroll
;             for (int t = 0; t < 4; ++t) hacc[t] = MFMA16(tr_frag(T + BS, RSC, 32 * s, 16 * (nb0 + t), lane), xf, hacc[t]);
;         }
; #pragma unroll
;         for (int t = 0; t < 4; ++t) { u32x2 w; w.x = pkbf(hacc[t][0], hacc[t][1]); w.y = pkbf(hacc[t][2], hacc[t][3]);
;             *(LAS u32x2*)(Hn + (16 * pbk + l15) * RSC + (16 * (nb0 + t) + 4 * quad) * 2) = w; }
.LBB0_1143:
	s_or_b64 exec, exec, s[0:1]
	v_add_u32_e32 v236, s62, v154
	v_add_u32_e32 v237, v97, v168
	v_add3_u32 v236, v236, v153, v167
	v_add_u32_e32 v238, v237, v93
	ds_read_b64_tr_b16 v[188:189], v236 offset:44032
	ds_read_b64_tr_b16 v[190:191], v236 offset:44608
	ds_read_b64_tr_b16 v[192:193], v238 offset:17408
	ds_read_b64_tr_b16 v[194:195], v238 offset:18496
	v_add_u32_e32 v238, v237, v138
	ds_read_b64_tr_b16 v[196:197], v238 offset:17408
	ds_read_b64_tr_b16 v[198:199], v238 offset:18496
	v_add_u32_e32 v238, v237, v139
	ds_read_b64_tr_b16 v[200:201], v238 offset:17408
	ds_read_b64_tr_b16 v[202:203], v238 offset:18496
	v_add_u32_e32 v238, v237, v140
	ds_read_b64_tr_b16 v[204:205], v238 offset:17408
	ds_read_b64_tr_b16 v[206:207], v238 offset:18496
	v_lshlrev_b32_e32 v54, 16, v126
	v_mul_f32_e32 v1, 0xbfb8aa3b, v54
	v_exp_f32_e32 v1, v1
	v_and_b32_e32 v55, 0xffff0000, v126
	v_lshlrev_b32_e32 v52, 16, v128
	v_and_b32_e32 v53, 0xffff0000, v128
	v_add_f32_e32 v1, 1.0, v1
	v_rcp_f32_e32 v56, v1
	v_mul_f32_e32 v1, 0xbfb8aa3b, v55
	v_exp_f32_e32 v1, v1
	v_pk_fma_f32 v[48:49], v[102:103], v[52:53], v[48:49]
	v_mov_b32_e32 v99, v3
	s_mulk_i32 s27, 0x4400
	v_add_f32_e32 v1, 1.0, v1
	v_rcp_f32_e32 v57, v1
	s_mov_b64 s[0:1], 0xf8000
	v_add_u32_e32 v106, 64, v106
	v_lshl_add_u64 v[112:113], v[112:113], 0, s[68:69]
	v_pk_mul_f32 v[52:53], v[56:57], v[54:55]
	v_lshlrev_b32_e32 v54, 16, v127
	v_mul_f32_e32 v1, 0xbfb8aa3b, v54
	v_exp_f32_e32 v1, v1
	v_and_b32_e32 v55, 0xffff0000, v127
	v_pk_mul_f32 v[48:49], v[52:53], v[48:49]
	v_lshlrev_b32_e32 v52, 16, v129
	v_add_f32_e32 v1, 1.0, v1
	v_rcp_f32_e32 v56, v1
	v_mul_f32_e32 v1, 0xbfb8aa3b, v55
	v_exp_f32_e32 v1, v1
	v_and_b32_e32 v53, 0xffff0000, v129
	v_pk_fma_f32 v[50:51], v[102:103], v[52:53], v[50:51]
	v_cvt_pk_bf16_f32 v48, v48, v49
	v_add_f32_e32 v1, 1.0, v1
	v_rcp_f32_e32 v57, v1
	v_mov_b32_e32 v1, 0x3fb8aa3b
	v_mul_f32_e32 v1, s11, v1
	v_lshl_add_u64 v[108:109], v[108:109], 0, s[30:31]
	v_pk_mul_f32 v[52:53], v[56:57], v[54:55]
	v_add_u32_e32 v239, v97, v169
	v_pk_mul_f32 v[50:51], v[52:53], v[50:51]
	v_add_u32_e32 v238, v239, v93
	v_cvt_pk_bf16_f32 v49, v50, v51
	v_lshl_add_u64 v[50:51], v[134:135], 0, v[98:99]
	global_store_dwordx2 v[50:51], v[48:49], off
	v_exp_f32_e32 v48, v1
	s_waitcnt lgkmcnt(5)
	ds_read_b64_tr_b16 v[208:209], v236 offset:48640
	ds_read_b64_tr_b16 v[210:211], v236 offset:49216
	ds_read_b64_tr_b16 v[212:213], v238 offset:17408
	ds_read_b64_tr_b16 v[214:215], v238 offset:18496
	v_add_u32_e32 v238, v239, v138
	ds_read_b64_tr_b16 v[216:217], v238 offset:17408
	ds_read_b64_tr_b16 v[218:219], v238 offset:18496
	v_add_u32_e32 v238, v239, v139
	ds_read_b64_tr_b16 v[220:221], v238 offset:17408
	ds_read_b64_tr_b16 v[222:223], v238 offset:18496
	v_add_u32_e32 v238, v239, v140
	ds_read_b64_tr_b16 v[232:233], v238 offset:17408
	ds_read_b64_tr_b16 v[234:235], v238 offset:18496
	v_lshl_add_u64 v[110:111], v[110:111], 0, s[30:31]
	v_pk_mul_f32 v[10:11], v[10:11], v[48:49] op_sel_hi:[1,0]
	v_pk_mul_f32 v[8:9], v[8:9], v[48:49] op_sel_hi:[1,0]
	v_pk_mul_f32 v[14:15], v[14:15], v[48:49] op_sel_hi:[1,0]
	v_pk_mul_f32 v[12:13], v[12:13], v[48:49] op_sel_hi:[1,0]
	v_pk_mul_f32 v[18:19], v[18:19], v[48:49] op_sel_hi:[1,0]
	v_pk_mul_f32 v[16:17], v[16:17], v[48:49] op_sel_hi:[1,0]
	v_pk_mul_f32 v[34:35], v[34:35], v[48:49] op_sel_hi:[1,0]
	v_pk_mul_f32 v[32:33], v[32:33], v[48:49] op_sel_hi:[1,0]
	s_waitcnt lgkmcnt(6)
	v_mfma_f32_16x16x32_bf16 v[8:11], v[192:195], v[188:191], v[8:11]
	v_mfma_f32_16x16x32_bf16 v[8:11], v[212:215], v[208:211], v[8:11]
	s_waitcnt lgkmcnt(4)
	v_mfma_f32_16x16x32_bf16 v[12:15], v[196:199], v[188:191], v[12:15]
	v_mfma_f32_16x16x32_bf16 v[12:15], v[216:219], v[208:211], v[12:15]
	s_waitcnt lgkmcnt(2)
	v_mfma_f32_16x16x32_bf16 v[16:19], v[200:203], v[188:191], v[16:19]
	v_mfma_f32_16x16x32_bf16 v[16:19], v[220:223], v[208:211], v[16:19]
	s_waitcnt lgkmcnt(0)
	v_mfma_f32_16x16x32_bf16 v[32:35], v[204:207], v[188:191], v[32:35]
	v_mfma_f32_16x16x32_bf16 v[32:35], v[232:235], v[208:211], v[32:35]
	v_lshl_add_u64 v[116:117], v[116:117], 0, s[0:1]
	v_lshl_add_u64 v[104:105], v[104:105], 0, s[30:31]
	s_add_i32 s100, s63, 2
	s_cmp_lt_u32 s100, s9
	s_cbranch_scc1 .Lssd_wait_g8
	s_waitcnt vmcnt(2)
	s_branch .Lssd_wait_gdone
